# tail-workgroup row phase: all MX/partial/residual loads of an iteration issued together at loop top (v_mov copies at old sites)
# baseline (speedup 1.0000x reference)
; __device__ __forceinline__ bf16* hrow16(unsigned char* ws, int r) { return (bf16*)(ws + WS_H16) + ((size_t)r << 10); }
; __device__ __forceinline__ void unpack8(const u32x4 w, float* v) { v[0] = bflo(w.x); v[1] = bfhi(w.x); v[2] = bflo(w.y); v[3] = bfhi(w.y); v[4] = bflo(w.z); v[5] = bfhi(w.z); v[6] = bflo(w.w); v[7] = bfhi(w.w); }
; __device__ __forceinline__ void row_res(KP kp, int gpost_in, int layer, bool has_next, int wid0, int row0, int row1, int b0, int nb, int tailp, bool pooled) {
;     ...
;     for (int base = row0 + ((int)blockIdx.x - b0) * 16 + wid; base < row1; base += nb * 16) {
;         float m[2][2][8], h[2][2][8]; float ss[2] = {0.f, 0.f};
; #pragma unroll
;         for (int r = 0; r < 2; ++r) { const int row = base + 8 * r; bf16* hp = hrow16(ws, row);
; #pragma unroll
;             for (int c = 0; c < 2; ++c) {
;                 if (tailp) { const bf16* t0 = (const bf16*)(ws + WS_MXT) + (size_t)(row - 128 * 256) * DM + c * 512 + lane * 8; unpack8(*(const u32x4*)t0, m[r][c]);
;                     for (int q = 1; q < tailp; ++q) { float m2[8]; unpack8(*(const u32x4*)(t0 + (size_t)q * 256 * 1024), m2);
; #pragma unroll
;                         for (int j = 0; j < 8; ++j) m[r][c][j] += m2[j]; } }
;                 else if (pooled) { const int t = row % LL, win = 2 << (c * 2 + (lane >> 5)), cnt = (t + 1) < win ? (t + 1) : win; const bf16* zp = MX + (size_t)row * DM + c * 512 + lane * 8;
;                     float z0[8], sum[8]; unpack8(*(const u32x4*)zp, z0);
; #pragma unroll
;                     for (int j = 0; j < 8; ++j) sum[j] = z0[j];
;                     for (int d = 1; d < cnt; ++d) { float zd[8]; unpack8(*(const u32x4*)(zp - (size_t)d * DM), zd);
; #pragma unroll
;                         for (int j = 0; j < 8; ++j) sum[j] += zd[j]; }
;                     const float inv = 1.0f / (float)cnt;
; #pragma unroll
;                     for (int j = 0; j < 8; ++j) m[r][c][j] = sum[j] * inv - z0[j]; }
;                 else { const u32x4 w = *(const u32x4*)(MX + (size_t)row * DM + c * 512 + lane * 8); unpack8(w, m[r][c]); }
;                 unpack8(*(const u32x4*)(hp + c * 512 + lane * 8), h[r][c]);
.LBB0_864:
	v_mul_hi_i32 v4, v38, s62
	v_lshrrev_b32_e32 v5, 31, v4
	v_ashrrev_i32_e32 v4, 7, v4
	v_add_u32_e32 v60, v4, v5
	v_ashrrev_i32_e32 v39, 31, v38
	v_mul_i32_i24_e32 v4, 0x810, v60
	v_lshlrev_b64 v[2:3], 11, v[38:39]
	v_sub_u32_e32 v4, v38, v4
	v_lshl_add_u64 v[6:7], v[46:47], 0, v[2:3]
	s_mov_b64 s[94:95], 0x4000
	v_lshl_add_u64 v[166:167], v[42:43], 0, v[2:3]
	v_lshl_add_u64 v[168:169], v[166:167], 0, s[94:95]
	global_load_dwordx4 v[150:153], v[166:167], off
	global_load_dwordx4 v[154:157], v[166:167], off offset:1024
	global_load_dwordx4 v[158:161], v[168:169], off
	global_load_dwordx4 v[162:165], v[168:169], off offset:1024
	s_cmp_lg_u64 s[26:27], 0
	s_cbranch_scc0 .Ltl_tailp
	v_lshl_add_u64 v[170:171], v[6:7], 0, s[94:95]
	global_load_dwordx4 v[118:121], v[6:7], off
	global_load_dwordx4 v[122:125], v[6:7], off offset:1024
	global_load_dwordx4 v[126:129], v[170:171], off
	global_load_dwordx4 v[130:133], v[170:171], off offset:1024
	s_branch .Ltl_done
.Ltl_tailp:
	v_lshl_add_u64 v[170:171], v[44:45], 0, v[2:3]
	s_mov_b32 s94, 0xfc000000
	s_mov_b32 s95, -1
	v_lshl_add_u64 v[170:171], v[170:171], 0, s[94:95]
	s_mov_b64 s[94:95], 0x80000
	v_lshl_add_u64 v[172:173], v[170:171], 0, s[94:95]
	global_load_dwordx4 v[118:121], v[170:171], off
	global_load_dwordx4 v[122:125], v[170:171], off offset:1024
	global_load_dwordx4 v[134:137], v[172:173], off
	global_load_dwordx4 v[138:141], v[172:173], off offset:1024
	s_mov_b64 s[94:95], 0x4000
	v_lshl_add_u64 v[170:171], v[170:171], 0, s[94:95]
	v_lshl_add_u64 v[172:173], v[172:173], 0, s[94:95]
	global_load_dwordx4 v[126:129], v[170:171], off
	global_load_dwordx4 v[130:133], v[170:171], off offset:1024
	global_load_dwordx4 v[142:145], v[172:173], off
	global_load_dwordx4 v[146:149], v[172:173], off offset:1024
.Ltl_done:
	v_add_u32_e32 v16, 1, v4
	s_mov_b64 s[4:5], -1
	s_and_b64 vcc, exec, s[26:27]
	s_cbranch_vccz .LBB0_874
	s_waitcnt vmcnt(0)
	v_mov_b64_e32 v[8:9], v[118:119]
	v_mov_b64_e32 v[10:11], v[120:121]
	s_and_b64 vcc, exec, s[28:29]
	s_waitcnt vmcnt(0)
	v_lshlrev_b32_e32 v22, 16, v8
	s_waitcnt lgkmcnt(0)
	v_and_b32_e32 v23, 0xffff0000, v8
	v_lshlrev_b32_e32 v24, 16, v9
	v_and_b32_e32 v25, 0xffff0000, v9
	v_lshlrev_b32_e32 v26, 16, v10
	v_and_b32_e32 v27, 0xffff0000, v10
	v_lshlrev_b32_e32 v28, 16, v11
	v_and_b32_e32 v29, 0xffff0000, v11
	s_cbranch_vccz .LBB0_867
	s_mov_b64 s[4:5], 0

; __device__ __forceinline__ bf16* hrow16(unsigned char* ws, int r) { return (bf16*)(ws + WS_H16) + ((size_t)r << 10); }
; __device__ __forceinline__ void unpack8(const u32x4 w, float* v) { v[0] = bflo(w.x); v[1] = bfhi(w.x); v[2] = bflo(w.y); v[3] = bfhi(w.y); v[4] = bflo(w.z); v[5] = bfhi(w.z); v[6] = bflo(w.w); v[7] = bfhi(w.w); }
; __device__ __forceinline__ void row_res(KP kp, int gpost_in, int layer, bool has_next, int wid0, int row0, int row1, int b0, int nb, int tailp, bool pooled) {
;     ...
;         for (int r = 0; r < 2; ++r) { const int row = base + 8 * r; bf16* hp = hrow16(ws, row);
; #pragma unroll
;             for (int c = 0; c < 2; ++c) {
;                 if (tailp) { const bf16* t0 = (const bf16*)(ws + WS_MXT) + (size_t)(row - 128 * 256) * DM + c * 512 + lane * 8; unpack8(*(const u32x4*)t0, m[r][c]);
;                     for (int q = 1; q < tailp; ++q) { float m2[8]; unpack8(*(const u32x4*)(t0 + (size_t)q * 256 * 1024), m2);
; #pragma unroll
;                         for (int j = 0; j < 8; ++j) m[r][c][j] += m2[j]; } }
;                 else if (pooled) { const int t = row % LL, win = 2 << (c * 2 + (lane >> 5)), cnt = (t + 1) < win ? (t + 1) : win; const bf16* zp = MX + (size_t)row * DM + c * 512 + lane * 8;
;                     float z0[8], sum[8]; unpack8(*(const u32x4*)zp, z0);
; #pragma unroll
;                     for (int j = 0; j < 8; ++j) sum[j] = z0[j];
;                     for (int d = 1; d < cnt; ++d) { float zd[8]; unpack8(*(const u32x4*)(zp - (size_t)d * DM), zd);
; #pragma unroll
;                         for (int j = 0; j < 8; ++j) sum[j] += zd[j]; }
;                     const float inv = 1.0f / (float)cnt;
; #pragma unroll
;                     for (int j = 0; j < 8; ++j) m[r][c][j] = sum[j] * inv - z0[j]; }
;                 else { const u32x4 w = *(const u32x4*)(MX + (size_t)row * DM + c * 512 + lane * 8); unpack8(w, m[r][c]); }
;                 unpack8(*(const u32x4*)(hp + c * 512 + lane * 8), h[r][c]);
.LBB0_874:
	s_andn2_b64 vcc, exec, s[4:5]
	s_brev_b32 s4, 63
	v_lshl_add_u64 v[10:11], v[44:45], 0, v[2:3]
	s_mov_b32 s5, -1
	v_lshl_add_u64 v[8:9], v[10:11], 0, s[4:5]
	s_cbranch_vccnz .LBB0_876
	v_add_co_u32_e32 v4, vcc, 0x80000, v8
	s_waitcnt vmcnt(0)
	v_mov_b64_e32 v[12:13], v[118:119]
	v_mov_b64_e32 v[14:15], v[120:121]
	s_nop 0
	v_addc_co_u32_e32 v5, vcc, 0, v9, vcc
	s_waitcnt vmcnt(0)
	v_mov_b64_e32 v[18:19], v[134:135]
	v_mov_b64_e32 v[20:21], v[136:137]
	s_waitcnt vmcnt(1)
	v_lshlrev_b32_e32 v4, 16, v12
	v_and_b32_e32 v5, 0xffff0000, v12
	s_waitcnt vmcnt(0)
	v_lshlrev_b32_e32 v22, 16, v18
	s_waitcnt lgkmcnt(0)
	v_and_b32_e32 v23, 0xffff0000, v18
	v_pk_add_f32 v[22:23], v[4:5], v[22:23]
	v_lshlrev_b32_e32 v4, 16, v13
	v_and_b32_e32 v5, 0xffff0000, v13
	v_lshlrev_b32_e32 v12, 16, v19
	v_and_b32_e32 v13, 0xffff0000, v19
	v_pk_add_f32 v[24:25], v[4:5], v[12:13]
	v_lshlrev_b32_e32 v4, 16, v14
	v_and_b32_e32 v5, 0xffff0000, v14
	v_lshlrev_b32_e32 v12, 16, v20
	v_and_b32_e32 v13, 0xffff0000, v20
	v_pk_add_f32 v[26:27], v[4:5], v[12:13]
	v_lshlrev_b32_e32 v4, 16, v15
	v_and_b32_e32 v5, 0xffff0000, v15
	v_lshlrev_b32_e32 v12, 16, v21
	v_and_b32_e32 v13, 0xffff0000, v21
	v_pk_add_f32 v[28:29], v[4:5], v[12:13]
.LBB0_876:
	v_lshl_add_u64 v[62:63], v[42:43], 0, v[2:3]
	s_waitcnt vmcnt(0)
	v_mov_b64_e32 v[2:3], v[150:151]
	v_mov_b64_e32 v[4:5], v[152:153]
	v_cndmask_b32_e64 v12, 0, 1, s[28:29]
	s_mov_b64 s[14:15], -1
	s_and_b64 vcc, exec, s[26:27]
	v_cmp_ne_u32_e64 s[4:5], 1, v12
	s_cbranch_vccz .LBB0_886
	s_waitcnt vmcnt(0)
	v_mov_b64_e32 v[12:13], v[122:123]
	v_mov_b64_e32 v[14:15], v[124:125]
	s_and_b64 vcc, exec, s[4:5]
	s_waitcnt vmcnt(0)
	v_lshlrev_b32_e32 v30, 16, v12
	v_and_b32_e32 v31, 0xffff0000, v12
	v_lshlrev_b32_e32 v32, 16, v13
	v_and_b32_e32 v33, 0xffff0000, v13
	v_lshlrev_b32_e32 v34, 16, v14
	v_and_b32_e32 v35, 0xffff0000, v14
	v_lshlrev_b32_e32 v36, 16, v15
	v_and_b32_e32 v37, 0xffff0000, v15
	s_cbranch_vccnz .LBB0_879
	s_mov_b64 s[14:15], 0

; __device__ __forceinline__ bf16* hrow16(unsigned char* ws, int r) { return (bf16*)(ws + WS_H16) + ((size_t)r << 10); }
; __device__ __forceinline__ void unpack8(const u32x4 w, float* v) { v[0] = bflo(w.x); v[1] = bfhi(w.x); v[2] = bflo(w.y); v[3] = bfhi(w.y); v[4] = bflo(w.z); v[5] = bfhi(w.z); v[6] = bflo(w.w); v[7] = bfhi(w.w); }
; __device__ __forceinline__ void row_res(KP kp, int gpost_in, int layer, bool has_next, int wid0, int row0, int row1, int b0, int nb, int tailp, bool pooled) {
;     ...
;         for (int r = 0; r < 2; ++r) { const int row = base + 8 * r; bf16* hp = hrow16(ws, row);
; #pragma unroll
;             for (int c = 0; c < 2; ++c) {
;                 if (tailp) { const bf16* t0 = (const bf16*)(ws + WS_MXT) + (size_t)(row - 128 * 256) * DM + c * 512 + lane * 8; unpack8(*(const u32x4*)t0, m[r][c]);
;                     for (int q = 1; q < tailp; ++q) { float m2[8]; unpack8(*(const u32x4*)(t0 + (size_t)q * 256 * 1024), m2);
; #pragma unroll
;                         for (int j = 0; j < 8; ++j) m[r][c][j] += m2[j]; } }
;                 else if (pooled) { const int t = row % LL, win = 2 << (c * 2 + (lane >> 5)), cnt = (t + 1) < win ? (t + 1) : win; const bf16* zp = MX + (size_t)row * DM + c * 512 + lane * 8;
;                     float z0[8], sum[8]; unpack8(*(const u32x4*)zp, z0);
; #pragma unroll
;                     for (int j = 0; j < 8; ++j) sum[j] = z0[j];
;                     for (int d = 1; d < cnt; ++d) { float zd[8]; unpack8(*(const u32x4*)(zp - (size_t)d * DM), zd);
; #pragma unroll
;                         for (int j = 0; j < 8; ++j) sum[j] += zd[j]; }
;                     const float inv = 1.0f / (float)cnt;
; #pragma unroll
;                     for (int j = 0; j < 8; ++j) m[r][c][j] = sum[j] * inv - z0[j]; }
;                 else { const u32x4 w = *(const u32x4*)(MX + (size_t)row * DM + c * 512 + lane * 8); unpack8(w, m[r][c]); }
;                 unpack8(*(const u32x4*)(hp + c * 512 + lane * 8), h[r][c]);
.LBB0_886:
	s_andn2_b64 vcc, exec, s[14:15]
	s_cbranch_vccnz .LBB0_888
	v_add_co_u32_e32 v6, vcc, 0x80000, v8
	s_waitcnt vmcnt(0)
	v_mov_b64_e32 v[12:13], v[122:123]
	v_mov_b64_e32 v[14:15], v[124:125]
	s_nop 0
	v_addc_co_u32_e32 v7, vcc, 0, v9, vcc
	s_waitcnt vmcnt(0)
	v_mov_b64_e32 v[6:7], v[138:139]
	v_mov_b64_e32 v[8:9], v[140:141]
	s_waitcnt vmcnt(1)
	v_lshlrev_b32_e32 v16, 16, v12
	v_and_b32_e32 v17, 0xffff0000, v12
	v_lshlrev_b32_e32 v12, 16, v13
	s_waitcnt vmcnt(0)
	v_lshlrev_b32_e32 v18, 16, v6
	v_and_b32_e32 v19, 0xffff0000, v6
	v_and_b32_e32 v13, 0xffff0000, v13
	v_lshlrev_b32_e32 v6, 16, v7
	v_and_b32_e32 v7, 0xffff0000, v7
	v_pk_add_f32 v[32:33], v[12:13], v[6:7]
	v_lshlrev_b32_e32 v6, 16, v14
	v_and_b32_e32 v7, 0xffff0000, v14
	v_lshlrev_b32_e32 v12, 16, v8
	v_and_b32_e32 v13, 0xffff0000, v8
	v_pk_add_f32 v[34:35], v[6:7], v[12:13]
	v_lshlrev_b32_e32 v6, 16, v15
	v_and_b32_e32 v7, 0xffff0000, v15
	v_lshlrev_b32_e32 v8, 16, v9
	v_and_b32_e32 v9, 0xffff0000, v9
	v_pk_add_f32 v[30:31], v[16:17], v[18:19]
	v_pk_add_f32 v[36:37], v[6:7], v[8:9]
.LBB0_888:
	s_waitcnt vmcnt(0)
	v_mov_b64_e32 v[6:7], v[154:155]
	v_mov_b64_e32 v[8:9], v[156:157]
	v_add_u32_e32 v64, 8, v38
	v_mul_hi_i32 v18, v64, s62
	v_lshrrev_b32_e32 v19, 31, v18
	v_ashrrev_i32_e32 v18, 7, v18
	v_add_u32_e32 v66, v18, v19
	v_ashrrev_i32_e32 v65, 31, v64
	v_mul_i32_i24_e32 v18, 0x810, v66
	v_ashrrev_i32_e32 v57, 31, v56
	v_lshlrev_b64 v[12:13], 11, v[64:65]
	v_sub_u32_e32 v18, v64, v18
	v_lshlrev_b64 v[14:15], 11, v[56:57]
	v_lshl_add_u64 v[16:17], v[46:47], 0, v[12:13]
	v_add_u32_e32 v57, 1, v18
	s_mov_b64 s[14:15], -1
	s_and_b64 vcc, exec, s[26:27]
	s_cbranch_vccz .LBB0_898
	s_waitcnt vmcnt(0)
	v_mov_b64_e32 v[18:19], v[126:127]
	v_mov_b64_e32 v[20:21], v[128:129]
	s_and_b64 vcc, exec, s[4:5]
	s_waitcnt vmcnt(0)
	v_lshlrev_b32_e32 v68, 16, v18
	v_and_b32_e32 v69, 0xffff0000, v18
	v_lshlrev_b32_e32 v70, 16, v19
	v_and_b32_e32 v71, 0xffff0000, v19
	v_lshlrev_b32_e32 v72, 16, v20
	v_and_b32_e32 v73, 0xffff0000, v20
	v_lshlrev_b32_e32 v74, 16, v21
	v_and_b32_e32 v75, 0xffff0000, v21
	s_cbranch_vccnz .LBB0_891
	s_mov_b64 s[14:15], 0

; __device__ __forceinline__ bf16* hrow16(unsigned char* ws, int r) { return (bf16*)(ws + WS_H16) + ((size_t)r << 10); }
; __device__ __forceinline__ void unpack8(const u32x4 w, float* v) { v[0] = bflo(w.x); v[1] = bfhi(w.x); v[2] = bflo(w.y); v[3] = bfhi(w.y); v[4] = bflo(w.z); v[5] = bfhi(w.z); v[6] = bflo(w.w); v[7] = bfhi(w.w); }
; __device__ __forceinline__ void row_res(KP kp, int gpost_in, int layer, bool has_next, int wid0, int row0, int row1, int b0, int nb, int tailp, bool pooled) {
;     ...
;         for (int r = 0; r < 2; ++r) { const int row = base + 8 * r; bf16* hp = hrow16(ws, row);
; #pragma unroll
;             for (int c = 0; c < 2; ++c) {
;                 if (tailp) { const bf16* t0 = (const bf16*)(ws + WS_MXT) + (size_t)(row - 128 * 256) * DM + c * 512 + lane * 8; unpack8(*(const u32x4*)t0, m[r][c]);
;                     for (int q = 1; q < tailp; ++q) { float m2[8]; unpack8(*(const u32x4*)(t0 + (size_t)q * 256 * 1024), m2);
; #pragma unroll
;                         for (int j = 0; j < 8; ++j) m[r][c][j] += m2[j]; } }
;                 else if (pooled) { const int t = row % LL, win = 2 << (c * 2 + (lane >> 5)), cnt = (t + 1) < win ? (t + 1) : win; const bf16* zp = MX + (size_t)row * DM + c * 512 + lane * 8;
;                     float z0[8], sum[8]; unpack8(*(const u32x4*)zp, z0);
; #pragma unroll
;                     for (int j = 0; j < 8; ++j) sum[j] = z0[j];
;                     for (int d = 1; d < cnt; ++d) { float zd[8]; unpack8(*(const u32x4*)(zp - (size_t)d * DM), zd);
; #pragma unroll
;                         for (int j = 0; j < 8; ++j) sum[j] += zd[j]; }
;                     const float inv = 1.0f / (float)cnt;
; #pragma unroll
;                     for (int j = 0; j < 8; ++j) m[r][c][j] = sum[j] * inv - z0[j]; }
;                 else { const u32x4 w = *(const u32x4*)(MX + (size_t)row * DM + c * 512 + lane * 8); unpack8(w, m[r][c]); }
;                 unpack8(*(const u32x4*)(hp + c * 512 + lane * 8), h[r][c]);
.LBB0_898:
	s_mov_b32 s6, 0xfc004000
	s_mov_b32 s7, -1
	s_andn2_b64 vcc, exec, s[14:15]
	v_lshl_add_u64 v[18:19], v[10:11], 0, s[6:7]
	s_cbranch_vccnz .LBB0_900
	v_add_co_u32_e32 v10, vcc, 0x80000, v18
	s_waitcnt vmcnt(0)
	v_mov_b64_e32 v[72:73], v[126:127]
	v_mov_b64_e32 v[74:75], v[128:129]
	s_nop 0
	v_addc_co_u32_e32 v11, vcc, 0, v19, vcc
	s_waitcnt vmcnt(0)
	v_mov_b64_e32 v[76:77], v[142:143]
	v_mov_b64_e32 v[78:79], v[144:145]
	s_waitcnt vmcnt(1)
	v_lshlrev_b32_e32 v10, 16, v72
	v_and_b32_e32 v11, 0xffff0000, v72
	s_waitcnt vmcnt(0)
	v_lshlrev_b32_e32 v20, 16, v76
	v_and_b32_e32 v21, 0xffff0000, v76
	v_pk_add_f32 v[68:69], v[10:11], v[20:21]
	v_lshlrev_b32_e32 v10, 16, v73
	v_and_b32_e32 v11, 0xffff0000, v73
	v_lshlrev_b32_e32 v20, 16, v77
	v_and_b32_e32 v21, 0xffff0000, v77
	v_pk_add_f32 v[70:71], v[10:11], v[20:21]
	v_lshlrev_b32_e32 v10, 16, v74
	v_and_b32_e32 v11, 0xffff0000, v74
	v_lshlrev_b32_e32 v20, 16, v78
	v_and_b32_e32 v21, 0xffff0000, v78
	v_pk_add_f32 v[72:73], v[10:11], v[20:21]
	v_lshlrev_b32_e32 v10, 16, v75
	v_and_b32_e32 v11, 0xffff0000, v75
	v_lshlrev_b32_e32 v20, 16, v79
	v_and_b32_e32 v21, 0xffff0000, v79
	v_pk_add_f32 v[74:75], v[10:11], v[20:21]
.LBB0_900:
	v_lshl_add_u64 v[76:77], v[42:43], 0, v[12:13]
	s_waitcnt vmcnt(0)
	v_mov_b64_e32 v[10:11], v[158:159]
	v_mov_b64_e32 v[12:13], v[160:161]
	s_mov_b64 s[14:15], -1
	s_and_b64 vcc, exec, s[26:27]
	s_cbranch_vccz .LBB0_910
	s_waitcnt vmcnt(0)
	v_mov_b64_e32 v[82:83], v[130:131]
	v_mov_b64_e32 v[84:85], v[132:133]
	s_and_b64 vcc, exec, s[4:5]
	s_waitcnt vmcnt(0)
	v_lshlrev_b32_e32 v78, 16, v82
	v_and_b32_e32 v79, 0xffff0000, v82
	v_lshlrev_b32_e32 v80, 16, v83
	v_and_b32_e32 v81, 0xffff0000, v83
	v_lshlrev_b32_e32 v82, 16, v84
	v_and_b32_e32 v83, 0xffff0000, v84
	v_lshlrev_b32_e32 v84, 16, v85
	v_and_b32_e32 v85, 0xffff0000, v85
	s_cbranch_vccnz .LBB0_903
	s_mov_b64 s[14:15], 0

; __device__ __forceinline__ float lane_xchg_(float v, int srclane) { return __builtin_bit_cast(float, __builtin_amdgcn_ds_bpermute(srclane << 2, __builtin_bit_cast(int, v))); }
; __device__ __forceinline__ void unpack8(const u32x4 w, float* v) { v[0] = bflo(w.x); v[1] = bfhi(w.x); v[2] = bflo(w.y); v[3] = bfhi(w.y); v[4] = bflo(w.z); v[5] = bfhi(w.z); v[6] = bflo(w.w); v[7] = bfhi(w.w); }
; __device__ __forceinline__ void row_res(KP kp, int gpost_in, int layer, bool has_next, int wid0, int row0, int row1, int b0, int nb, int tailp, bool pooled) {
;     ...
;                 if (tailp) { const bf16* t0 = (const bf16*)(ws + WS_MXT) + (size_t)(row - 128 * 256) * DM + c * 512 + lane * 8; unpack8(*(const u32x4*)t0, m[r][c]);
;                     for (int q = 1; q < tailp; ++q) { float m2[8]; unpack8(*(const u32x4*)(t0 + (size_t)q * 256 * 1024), m2);
; #pragma unroll
;                         for (int j = 0; j < 8; ++j) m[r][c][j] += m2[j]; } }
;                 else if (pooled) { const int t = row % LL, win = 2 << (c * 2 + (lane >> 5)), cnt = (t + 1) < win ? (t + 1) : win; const bf16* zp = MX + (size_t)row * DM + c * 512 + lane * 8;
;                     float z0[8], sum[8]; unpack8(*(const u32x4*)zp, z0);
; #pragma unroll
;                     for (int j = 0; j < 8; ++j) sum[j] = z0[j];
;                     for (int d = 1; d < cnt; ++d) { float zd[8]; unpack8(*(const u32x4*)(zp - (size_t)d * DM), zd);
; #pragma unroll
;                         for (int j = 0; j < 8; ++j) sum[j] += zd[j]; }
;                     const float inv = 1.0f / (float)cnt;
; #pragma unroll
;                     for (int j = 0; j < 8; ++j) m[r][c][j] = sum[j] * inv - z0[j]; }
;                 else { const u32x4 w = *(const u32x4*)(MX + (size_t)row * DM + c * 512 + lane * 8); unpack8(w, m[r][c]); }
;                 unpack8(*(const u32x4*)(hp + c * 512 + lane * 8), h[r][c]);
; #pragma unroll
;                 for (int j = 0; j < 8; ++j) ss[r] += m[r][c][j] * m[r][c][j]; } }
; #pragma unroll
;         for (int o = 32; o > 0; o >>= 1) { const float a = lane_xchg_(ss[0], lane ^ o), b = lane_xchg_(ss[1], lane ^ o); ss[0] += a; ss[1] += b; }
.LBB0_910:
	s_andn2_b64 vcc, exec, s[14:15]
	s_cbranch_vccnz .LBB0_912
	s_waitcnt vmcnt(0)
	v_mov_b64_e32 v[14:15], v[130:131]
	v_mov_b64_e32 v[16:17], v[132:133]
	v_add_co_u32_e32 v18, vcc, 0x80000, v18
	s_waitcnt vmcnt(0)
	v_lshlrev_b32_e32 v78, 16, v14
	v_addc_co_u32_e32 v19, vcc, 0, v19, vcc
	s_waitcnt vmcnt(0)
	v_mov_b64_e32 v[18:19], v[146:147]
	v_mov_b64_e32 v[20:21], v[148:149]
	v_and_b32_e32 v79, 0xffff0000, v14
	v_lshlrev_b32_e32 v14, 16, v15
	v_and_b32_e32 v15, 0xffff0000, v15
	s_waitcnt vmcnt(0)
	v_lshlrev_b32_e32 v80, 16, v18
	v_and_b32_e32 v81, 0xffff0000, v18
	v_lshlrev_b32_e32 v18, 16, v19
	v_and_b32_e32 v19, 0xffff0000, v19
	v_pk_add_f32 v[78:79], v[78:79], v[80:81]
	v_pk_add_f32 v[80:81], v[14:15], v[18:19]
	v_lshlrev_b32_e32 v14, 16, v16
	v_and_b32_e32 v15, 0xffff0000, v16
	v_lshlrev_b32_e32 v18, 16, v20
	v_and_b32_e32 v19, 0xffff0000, v20
	v_pk_add_f32 v[82:83], v[14:15], v[18:19]
	v_lshlrev_b32_e32 v14, 16, v17
	v_and_b32_e32 v15, 0xffff0000, v17
	v_lshlrev_b32_e32 v16, 16, v21
	v_and_b32_e32 v17, 0xffff0000, v21
	v_pk_add_f32 v[84:85], v[14:15], v[16:17]
.LBB0_912:
	s_waitcnt vmcnt(0)
	v_lshlrev_b32_e32 v86, 16, v10
	v_and_b32_e32 v87, 0xffff0000, v10
	v_lshlrev_b32_e32 v88, 16, v11
	v_and_b32_e32 v89, 0xffff0000, v11
	s_waitcnt lgkmcnt(0)
	v_pk_mul_f32 v[10:11], v[22:23], v[22:23]
	v_lshlrev_b32_e32 v90, 16, v12
	v_and_b32_e32 v91, 0xffff0000, v12
	v_lshlrev_b32_e32 v92, 16, v13
	v_and_b32_e32 v93, 0xffff0000, v13
	v_pk_mul_f32 v[12:13], v[24:25], v[24:25]
	v_add_f32_e32 v10, v11, v10
	v_pk_mul_f32 v[14:15], v[68:69], v[68:69]
	v_add_f32_e32 v10, v12, v10
	v_pk_mul_f32 v[16:17], v[70:71], v[70:71]
	v_pk_mul_f32 v[110:111], v[26:27], v[26:27]
	v_add_f32_e32 v10, v13, v10
	v_add_f32_e32 v14, v15, v14
	v_add_f32_e32 v10, v110, v10
	v_add_f32_e32 v14, v16, v14
	v_pk_mul_f32 v[18:19], v[72:73], v[72:73]
	v_pk_mul_f32 v[112:113], v[28:29], v[28:29]
	v_add_f32_e32 v10, v111, v10
	v_add_f32_e32 v14, v17, v14
	v_add_f32_e32 v10, v112, v10
	v_add_f32_e32 v14, v18, v14
	v_pk_mul_f32 v[20:21], v[74:75], v[74:75]
	v_lshlrev_b32_e32 v94, 16, v6
	v_and_b32_e32 v95, 0xffff0000, v6
	v_lshlrev_b32_e32 v96, 16, v7
	v_and_b32_e32 v97, 0xffff0000, v7
	v_pk_mul_f32 v[6:7], v[30:31], v[30:31]
	v_add_f32_e32 v10, v113, v10
	v_add_f32_e32 v14, v19, v14
	v_add_f32_e32 v6, v10, v6
	v_add_f32_e32 v14, v20, v14
	v_lshlrev_b32_e32 v100, 16, v8
	v_and_b32_e32 v101, 0xffff0000, v8
	v_lshlrev_b32_e32 v98, 16, v9
	v_and_b32_e32 v99, 0xffff0000, v9
	v_pk_mul_f32 v[8:9], v[32:33], v[32:33]
	v_add_f32_e32 v6, v7, v6
	v_pk_mul_f32 v[110:111], v[78:79], v[78:79]
	v_add_f32_e32 v14, v21, v14
	v_add_f32_e32 v6, v8, v6
	v_add_f32_e32 v14, v14, v110
	v_pk_mul_f32 v[114:115], v[34:35], v[34:35]
	v_add_f32_e32 v6, v9, v6
	v_pk_mul_f32 v[112:113], v[80:81], v[80:81]
	v_add_f32_e32 v14, v111, v14
	v_add_f32_e32 v6, v114, v6
	v_add_f32_e32 v14, v112, v14
	v_pk_mul_f32 v[116:117], v[36:37], v[36:37]
	v_add_f32_e32 v6, v115, v6
	v_pk_mul_f32 v[114:115], v[82:83], v[82:83]
	v_add_f32_e32 v14, v113, v14
	v_add_f32_e32 v6, v116, v6
	v_add_f32_e32 v14, v114, v14
	v_add_f32_e32 v57, v117, v6
	v_pk_mul_f32 v[116:117], v[84:85], v[84:85]
	v_add_f32_e32 v14, v115, v14
	v_add_f32_e32 v14, v116, v14
	v_add_f32_e32 v14, v117, v14
	ds_bpermute_b32 v15, v103, v57
	ds_bpermute_b32 v16, v103, v14
	v_lshlrev_b32_e32 v6, 16, v2
	v_and_b32_e32 v7, 0xffff0000, v2
	v_lshlrev_b32_e32 v8, 16, v3
	s_waitcnt lgkmcnt(1)
	v_add_f32_e32 v15, v57, v15
	s_waitcnt lgkmcnt(0)
	v_add_f32_e32 v14, v14, v16
	ds_bpermute_b32 v16, v104, v15
	ds_bpermute_b32 v17, v104, v14
	v_and_b32_e32 v9, 0xffff0000, v3
	v_lshlrev_b32_e32 v10, 16, v4
	v_and_b32_e32 v11, 0xffff0000, v4
	s_waitcnt lgkmcnt(1)
	v_add_f32_e32 v15, v15, v16
	s_waitcnt lgkmcnt(0)
	v_add_f32_e32 v14, v14, v17
	ds_bpermute_b32 v16, v105, v15
	ds_bpermute_b32 v17, v105, v14
	v_lshlrev_b32_e32 v12, 16, v5
	v_and_b32_e32 v13, 0xffff0000, v5
	s_waitcnt vmcnt(0)
	v_mov_b64_e32 v[2:3], v[162:163]
	v_mov_b64_e32 v[4:5], v[164:165]
	s_waitcnt lgkmcnt(1)
	v_add_f32_e32 v15, v15, v16
	s_waitcnt lgkmcnt(0)
	v_add_f32_e32 v14, v14, v17
	ds_bpermute_b32 v16, v106, v15
	ds_bpermute_b32 v17, v106, v14
	s_waitcnt lgkmcnt(1)
	v_add_f32_e32 v15, v15, v16
	s_waitcnt lgkmcnt(0)
	v_add_f32_e32 v14, v14, v17
	ds_bpermute_b32 v16, v107, v15
	ds_bpermute_b32 v17, v107, v14
	s_waitcnt lgkmcnt(1)
	v_add_f32_e32 v15, v15, v16
	s_waitcnt lgkmcnt(0)
	v_add_f32_e32 v14, v14, v17
	ds_bpermute_b32 v16, v108, v15
	ds_bpermute_b32 v17, v108, v14
	s_waitcnt lgkmcnt(1)
	v_add_f32_e32 v15, v15, v16
	s_waitcnt lgkmcnt(0)
; __device__ __forceinline__ unsigned pk2(float lo, float hi) { const pk_f32x2 v = {lo, hi}; const pk_bf16x2 b = __builtin_convertvector(v, pk_bf16x2); return __builtin_bit_cast(unsigned, b); }
; __device__ __forceinline__ float lane_xchg_(float v, int srclane) { return __builtin_bit_cast(float, __builtin_amdgcn_ds_bpermute(srclane << 2, __builtin_bit_cast(int, v))); }
; __device__ __forceinline__ void row_res(KP kp, int gpost_in, int layer, bool has_next, int wid0, int row0, int row1, int b0, int nb, int tailp, bool pooled) {
;     ...
;         for (int r = 0; r < 2; ++r) { const float rstd = 1.0f / sqrtf(ss[r] * (1.0f / DM) + NORM_EPS);
; #pragma unroll
;             for (int c = 0; c < 2; ++c) { const int col = c * 512 + lane * 8; const f32x4 ga = *(const f32x4*)(g_post + col), gb = *(const f32x4*)(g_post + col + 4);
; #pragma unroll
;                 for (int j = 0; j < 8; ++j) { h[r][c][j] += m[r][c][j] * rstd * (j < 4 ? ga[j & 3] : gb[j & 3]); s2[r] += h[r][c][j] * h[r][c][j]; } } }
;         if (has_next) {
; #pragma unroll
;             for (int o = 32; o > 0; o >>= 1) { const float a = lane_xchg_(s2[0], lane ^ o), b = lane_xchg_(s2[1], lane ^ o); s2[0] += a; s2[1] += b; }
; #pragma unroll
;             for (int r = 0; r < 2; ++r) { const int row = base + 8 * r; bf16* hp = hrow16(ws, row);
; #pragma unroll
;                 for (int c = 0; c < 2; ++c) { u32x4 hw; hw.x = pk2(h[r][c][0], h[r][c][1]); hw.y = pk2(h[r][c][2], h[r][c][3]); hw.z = pk2(h[r][c][4], h[r][c][5]); hw.w = pk2(h[r][c][6], h[r][c][7]);
;                     *(u32x4*)(hp + c * 512 + lane * 8) = hw; }
;                 if (lane == 0) rsd[row] = 1.0f / sqrtf(s2[r] * (1.0f / DM) + NORM_EPS); }
;         } else {
; #pragma unroll
;             for (int r = 0; r < 2; ++r) { const int row = base + 8 * r; const int b = row / LL, t = row - b * LL;
;                 if (t >= NMETA) { float* op = out + (((size_t)b * SEQ + (t - NMETA)) << 10);
; #pragma unroll
;                     for (int c = 0; c < 2; ++c) { const int col = c * 512 + lane * 8;
;                         __builtin_nontemporal_store((f32x4){h[r][c][0], h[r][c][1], h[r][c][2], h[r][c][3]}, (f32x4*)(op + col)); __builtin_nontemporal_store((f32x4){h[r][c][4], h[r][c][5], h[r][c][6], h[r][c][7]}, (f32x4*)(op + col + 4)); } } }
	v_add_f32_e32 v57, v14, v17
	v_fmamk_f32 v14, v15, 0x3a800000, v242
	v_cmp_gt_f32_e32 vcc, s80, v14
	v_mul_f32_e32 v15, 0x4f800000, v14
	v_fmamk_f32 v57, v57, 0x3a800000, v242
	v_cndmask_b32_e32 v14, v14, v15, vcc
	v_sqrt_f32_e32 v15, v14
	v_mul_f32_e32 v61, 0x4f800000, v57
	v_add_u32_e32 v16, -1, v15
	v_fma_f32 v17, -v16, v15, v14
	v_cmp_ge_f32_e64 s[4:5], 0, v17
	v_add_u32_e32 v17, 1, v15
	s_nop 0
	v_cndmask_b32_e64 v16, v15, v16, s[4:5]
	v_fma_f32 v15, -v17, v15, v14
	v_cmp_lt_f32_e64 s[4:5], 0, v15
	s_nop 1
	v_cndmask_b32_e64 v15, v16, v17, s[4:5]
	v_mul_f32_e32 v16, 0x37800000, v15
	v_cndmask_b32_e32 v15, v15, v16, vcc
	v_cmp_class_f32_e32 vcc, v14, v243
	s_nop 1
	v_cndmask_b32_e32 v14, v15, v14, vcc
	v_div_scale_f32 v15, s[4:5], v14, v14, 1.0
	v_rcp_f32_e32 v16, v15
	s_nop 0
	v_fma_f32 v17, -v15, v16, 1.0
	v_fmac_f32_e32 v16, v17, v16
	v_div_scale_f32 v17, vcc, 1.0, v14, 1.0
	v_mul_f32_e32 v18, v17, v16
	v_fma_f32 v19, -v15, v18, v17
	v_fmac_f32_e32 v18, v19, v16
	v_fma_f32 v15, -v15, v18, v17
	v_div_fmas_f32 v15, v15, v16, v18
	v_div_fixup_f32 v102, v15, v14, 1.0
	global_load_dwordx4 v[14:17], v[48:49], off offset:16
	global_load_dwordx4 v[18:21], v[48:49], off
	v_pk_mul_f32 v[22:23], v[22:23], v[102:103] op_sel_hi:[1,0]
	v_cmp_gt_f32_e32 vcc, s80, v57
	v_pk_mul_f32 v[30:31], v[30:31], v[102:103] op_sel_hi:[1,0]
	v_pk_mul_f32 v[32:33], v[32:33], v[102:103] op_sel_hi:[1,0]
	v_cndmask_b32_e32 v57, v57, v61, vcc
	v_sqrt_f32_e32 v61, v57
	v_pk_mul_f32 v[34:35], v[34:35], v[102:103] op_sel_hi:[1,0]
	v_pk_mul_f32 v[36:37], v[36:37], v[102:103] op_sel_hi:[1,0]
	v_add_u32_e32 v67, -1, v61
	s_waitcnt vmcnt(0)
	v_pk_fma_f32 v[6:7], v[18:19], v[22:23], v[6:7]
	v_pk_mul_f32 v[22:23], v[24:25], v[102:103] op_sel_hi:[1,0]
	s_nop 0
	v_pk_fma_f32 v[8:9], v[20:21], v[22:23], v[8:9]
	v_pk_mul_f32 v[22:23], v[26:27], v[102:103] op_sel_hi:[1,0]
	s_nop 0
	v_pk_fma_f32 v[10:11], v[14:15], v[22:23], v[10:11]
	v_pk_mul_f32 v[22:23], v[28:29], v[102:103] op_sel_hi:[1,0]
	s_nop 0
	v_pk_fma_f32 v[12:13], v[16:17], v[22:23], v[12:13]
	global_load_dwordx4 v[22:25], v[48:49], off offset:2064
	global_load_dwordx4 v[26:29], v[48:49], off offset:2048
	s_waitcnt vmcnt(1)
	v_pk_fma_f32 v[34:35], v[22:23], v[34:35], v[100:101]
	s_waitcnt vmcnt(0)
	v_pk_fma_f32 v[30:31], v[26:27], v[30:31], v[94:95]
	v_fma_f32 v94, -v67, v61, v57
	v_cmp_ge_f32_e64 s[4:5], 0, v94
	v_add_u32_e32 v94, 1, v61
	v_pk_fma_f32 v[32:33], v[28:29], v[32:33], v[96:97]
	v_cndmask_b32_e64 v67, v61, v67, s[4:5]
	v_fma_f32 v61, -v94, v61, v57
	v_cmp_lt_f32_e64 s[4:5], 0, v61
	v_pk_fma_f32 v[36:37], v[24:25], v[36:37], v[98:99]
	s_nop 0
	v_cndmask_b32_e64 v61, v67, v94, s[4:5]
	v_mul_f32_e32 v67, 0x37800000, v61
	v_cndmask_b32_e32 v61, v61, v67, vcc
	v_cmp_class_f32_e32 vcc, v57, v243
	s_nop 1
	v_cndmask_b32_e32 v57, v61, v57, vcc
	v_div_scale_f32 v61, s[4:5], v57, v57, 1.0
	v_rcp_f32_e32 v67, v61
	s_mov_b64 s[4:5], -1
	v_fma_f32 v94, -v61, v67, 1.0
	v_fmac_f32_e32 v67, v94, v67
	v_div_scale_f32 v94, vcc, 1.0, v57, 1.0
	v_mul_f32_e32 v95, v94, v67
	v_fma_f32 v96, -v61, v95, v94
	v_fmac_f32_e32 v95, v96, v67
	v_fma_f32 v61, -v61, v95, v94
	v_div_fmas_f32 v61, v61, v67, v95
	v_div_fixup_f32 v94, v61, v57, 1.0
	v_pk_mul_f32 v[68:69], v[68:69], v[94:95] op_sel_hi:[1,0]
	s_andn2_b64 vcc, exec, s[34:35]
	v_pk_fma_f32 v[18:19], v[18:19], v[68:69], v[86:87]
	v_pk_mul_f32 v[68:69], v[70:71], v[94:95] op_sel_hi:[1,0]
	v_pk_mul_f32 v[70:71], v[78:79], v[94:95] op_sel_hi:[1,0]
	v_pk_fma_f32 v[20:21], v[20:21], v[68:69], v[88:89]
	v_pk_mul_f32 v[68:69], v[72:73], v[94:95] op_sel_hi:[1,0]
	s_nop 0
	v_pk_fma_f32 v[14:15], v[14:15], v[68:69], v[90:91]
	v_pk_mul_f32 v[68:69], v[74:75], v[94:95] op_sel_hi:[1,0]
	s_nop 0
	v_pk_fma_f32 v[16:17], v[16:17], v[68:69], v[92:93]
	v_lshlrev_b32_e32 v68, 16, v2
	v_and_b32_e32 v69, 0xffff0000, v2
	v_pk_fma_f32 v[26:27], v[26:27], v[70:71], v[68:69]
	v_lshlrev_b32_e32 v2, 16, v3
	v_and_b32_e32 v3, 0xffff0000, v3
	v_pk_mul_f32 v[68:69], v[80:81], v[94:95] op_sel_hi:[1,0]
	s_nop 0
	v_pk_fma_f32 v[28:29], v[28:29], v[68:69], v[2:3]
	v_lshlrev_b32_e32 v2, 16, v4
	v_and_b32_e32 v3, 0xffff0000, v4
	v_pk_mul_f32 v[68:69], v[82:83], v[94:95] op_sel_hi:[1,0]
	v_lshlrev_b32_e32 v4, 16, v5
	v_pk_fma_f32 v[2:3], v[22:23], v[68:69], v[2:3]
	v_and_b32_e32 v5, 0xffff0000, v5
	v_pk_mul_f32 v[22:23], v[84:85], v[94:95] op_sel_hi:[1,0]
	s_nop 0
	v_pk_fma_f32 v[4:5], v[24:25], v[22:23], v[4:5]
	s_cbranch_vccnz .LBB0_918
	v_mad_i32_i24 v23, v60, s84, v38
	v_cmp_lt_i32_e32 vcc, 15, v23
	v_lshlrev_b32_e32 v22, 2, v40
	s_and_saveexec_b64 s[4:5], vcc
	s_cbranch_execz .LBB0_915
	v_ashrrev_i32_e32 v61, 31, v60
	v_add_u32_e32 v24, -16, v23
	v_mov_b32_e32 v25, v0
	v_lshlrev_b64 v[60:61], 23, v[60:61]
	v_lshl_add_u64 v[60:61], s[8:9], 0, v[60:61]
	v_lshlrev_b64 v[24:25], 12, v[24:25]
	v_lshl_add_u64 v[24:25], v[60:61], 0, v[24:25]
	v_mov_b32_e32 v23, v0
	v_lshl_add_u64 v[24:25], v[24:25], 0, v[22:23]
	global_store_dwordx4 v[24:25], v[6:9], off nt
	global_store_dwordx4 v[24:25], v[10:13], off offset:16 nt
	global_store_dwordx4 v[24:25], v[30:33], off offset:2048 nt
	global_store_dwordx4 v[24:25], v[34:37], off offset:2064 nt
